# attention loops: per-tile K/V DMA address selection hoisted (persistent per-lane addresses + strides in VGPRs), 79/62 -> 32/30 instr
# speedup vs baseline: 1.0105x; 1.0006x over previous
.LBB0_621:
	s_nop 10
	v_max_f32_e32 v32, v1, v1
	v_max_f32_e32 v33, v17, v17
	v_max_f32_e32 v32, v33, v32
	v_max_f32_e32 v33, v2, v2
	v_max_f32_e32 v34, v18, v18
	v_max_f32_e32 v33, v34, v33
	v_max_f32_e32 v34, v3, v3
	v_max_f32_e32 v35, v19, v19
	v_max3_f32 v32, v16, v0, v32
	v_max_f32_e32 v34, v35, v34
	v_max3_f32 v32, v32, v33, v34
	v_max_f32_e32 v33, v4, v4
	v_max_f32_e32 v34, v20, v20
	v_max_f32_e32 v33, v34, v33
	v_max_f32_e32 v34, v5, v5
	v_max_f32_e32 v35, v21, v21
	v_max_f32_e32 v34, v35, v34
	v_max3_f32 v32, v32, v33, v34
	v_max_f32_e32 v33, v6, v6
	v_max_f32_e32 v34, v22, v22
	v_max_f32_e32 v33, v34, v33
	v_max_f32_e32 v34, v7, v7
	v_max_f32_e32 v35, v23, v23
	v_max_f32_e32 v34, v35, v34
	v_max3_f32 v32, v32, v33, v34
	v_max_f32_e32 v33, v8, v8
	v_max_f32_e32 v34, v24, v24
	v_max_f32_e32 v33, v34, v33
	v_max_f32_e32 v34, v9, v9
	v_max_f32_e32 v35, v25, v25
	v_max_f32_e32 v34, v35, v34
	v_max3_f32 v32, v32, v33, v34
	v_max_f32_e32 v33, v10, v10
	v_max_f32_e32 v34, v26, v26
	v_max_f32_e32 v33, v34, v33
	v_max_f32_e32 v34, v11, v11
	v_max_f32_e32 v35, v27, v27
	v_max_f32_e32 v34, v35, v34
	v_max3_f32 v32, v32, v33, v34
	v_max_f32_e32 v33, v12, v12
	v_max_f32_e32 v34, v28, v28
	v_max_f32_e32 v33, v34, v33
	v_max_f32_e32 v34, v13, v13
	v_max_f32_e32 v35, v29, v29
	v_max_f32_e32 v34, v35, v34
	v_max3_f32 v32, v32, v33, v34
	v_max_f32_e32 v33, v14, v14
	v_max_f32_e32 v34, v30, v30
	v_max_f32_e32 v33, v34, v33
	v_max_f32_e32 v34, v15, v15
	v_max_f32_e32 v35, v31, v31
	v_max_f32_e32 v34, v35, v34
	v_max3_f32 v32, v32, v33, v34
	v_mov_b32_e32 v33, v32
	s_nop 1
	v_permlane32_swap_b32_e32 v32, v33
	v_max_f32_e32 v33, v33, v33
	v_max_f32_e32 v32, v32, v32
	v_max_f32_e32 v64, v32, v33
	v_sub_f32_e32 v32, v0, v64
	v_sub_f32_e32 v0, v16, v64
	v_sub_f32_e32 v33, v1, v64
	v_sub_f32_e32 v1, v17, v64
	v_exp_f32_e32 v0, v0
	v_sub_f32_e32 v34, v2, v64
	v_sub_f32_e32 v2, v18, v64
	v_exp_f32_e32 v1, v1
	v_sub_f32_e32 v35, v3, v64
	v_sub_f32_e32 v3, v19, v64
	v_exp_f32_e32 v2, v2
	v_sub_f32_e32 v36, v4, v64
	v_sub_f32_e32 v4, v20, v64
	v_exp_f32_e32 v3, v3
	v_sub_f32_e32 v37, v5, v64
	v_sub_f32_e32 v5, v21, v64
	v_add_f32_e32 v16, 0, v0
	v_exp_f32_e32 v4, v4
	v_sub_f32_e32 v38, v6, v64
	v_sub_f32_e32 v6, v22, v64
	v_add_f32_e32 v16, v1, v16
	v_exp_f32_e32 v5, v5
	v_sub_f32_e32 v39, v7, v64
	v_sub_f32_e32 v7, v23, v64
	v_add_f32_e32 v16, v2, v16
	v_exp_f32_e32 v6, v6
	v_sub_f32_e32 v65, v8, v64
	v_sub_f32_e32 v8, v24, v64
	v_add_f32_e32 v16, v3, v16
	v_exp_f32_e32 v7, v7
	v_sub_f32_e32 v98, v9, v64
	v_sub_f32_e32 v9, v25, v64
	v_add_f32_e32 v16, v4, v16
	v_exp_f32_e32 v8, v8
	v_sub_f32_e32 v99, v10, v64
	v_sub_f32_e32 v10, v26, v64
	v_add_f32_e32 v16, v5, v16
	v_exp_f32_e32 v9, v9
	v_sub_f32_e32 v100, v11, v64
	v_sub_f32_e32 v11, v27, v64
	v_add_f32_e32 v16, v6, v16
	v_exp_f32_e32 v10, v10
	v_sub_f32_e32 v101, v12, v64
	v_sub_f32_e32 v12, v28, v64
	v_add_f32_e32 v16, v7, v16
	v_exp_f32_e32 v11, v11
	v_sub_f32_e32 v102, v13, v64
	v_sub_f32_e32 v13, v29, v64
	v_add_f32_e32 v16, v8, v16
	v_exp_f32_e32 v12, v12
	v_sub_f32_e32 v103, v14, v64
	v_sub_f32_e32 v14, v30, v64
	v_add_f32_e32 v16, v9, v16
	v_exp_f32_e32 v13, v13
	v_sub_f32_e32 v104, v15, v64
	v_sub_f32_e32 v15, v31, v64
	v_add_f32_e32 v16, v10, v16
	v_exp_f32_e32 v14, v14
	v_add_f32_e32 v16, v11, v16
	v_exp_f32_e32 v15, v15
	v_add_f32_e32 v16, v12, v16
	v_add_f32_e32 v16, v13, v16
	v_mul_u32_u24_e32 v143, 0x90, v140
	v_and_b32_e32 v163, 32, v141
	v_add_f32_e32 v16, v14, v16
	v_add_f32_e32 v16, v15, v16
	s_waitcnt vmcnt(5) lgkmcnt(0)
	s_barrier
	v_add3_u32 v105, 0, v143, v163
	v_add_f32_e32 v107, 0, v16
	v_cvt_pk_bf16_f32 v16, v0, v1
	v_cvt_pk_bf16_f32 v17, v2, v3
	v_cvt_pk_bf16_f32 v18, v4, v5
	v_cvt_pk_bf16_f32 v19, v6, v7
	ds_read_b128 v[0:3], v105 offset:18432
	ds_read_b128 v[20:23], v105 offset:18448
	ds_read_b128 v[4:7], v105 offset:23040
	ds_read_b128 v[24:27], v105 offset:23056
	v_cvt_pk_bf16_f32 v66, v8, v9
	v_cvt_pk_bf16_f32 v67, v10, v11
	v_cvt_pk_bf16_f32 v68, v12, v13
	v_cvt_pk_bf16_f32 v69, v14, v15
	ds_read_b128 v[28:31], v105 offset:27648
	ds_read_b128 v[70:73], v105 offset:27664
	ds_read_b128 v[74:77], v105 offset:32256
	ds_read_b128 v[78:81], v105 offset:32272
	s_waitcnt lgkmcnt(0)
	v_mfma_f32_32x32x16_bf16 v[48:63], v[0:3], v[16:19], 0
	v_exp_f32_e32 v106, v32
	v_exp_f32_e32 v108, v33
	v_exp_f32_e32 v109, v34
	v_exp_f32_e32 v110, v35
	v_mfma_f32_32x32x16_bf16 v[0:15], v[4:7], v[16:19], 0
	v_mfma_f32_32x32x16_bf16 v[48:63], v[20:23], v[66:69], v[48:63]
	v_exp_f32_e32 v111, v36
	v_exp_f32_e32 v128, v37
	v_exp_f32_e32 v129, v38
	v_exp_f32_e32 v130, v39
	v_mfma_f32_32x32x16_bf16 v[0:15], v[24:27], v[66:69], v[0:15]
	ds_read_b128 v[82:85], v105 offset:18496
	ds_read_b128 v[86:89], v105 offset:18512
	ds_read_b128 v[90:93], v105 offset:23104
	ds_read_b128 v[94:97], v105 offset:23120
	v_mfma_f32_32x32x16_bf16 v[32:47], v[28:31], v[16:19], 0
	v_exp_f32_e32 v65, v65
	v_exp_f32_e32 v131, v98
	v_exp_f32_e32 v132, v99
	v_exp_f32_e32 v133, v100
	v_mfma_f32_32x32x16_bf16 v[16:31], v[74:77], v[16:19], 0
	v_mfma_f32_32x32x16_bf16 v[32:47], v[70:73], v[66:69], v[32:47]
	v_exp_f32_e32 v134, v101
	v_exp_f32_e32 v135, v102
	v_exp_f32_e32 v136, v103
	v_exp_f32_e32 v137, v104
	v_cvt_pk_bf16_f32 v70, v65, v131
	v_cvt_pk_bf16_f32 v71, v132, v133
	v_cvt_pk_bf16_f32 v72, v134, v135
	v_mfma_f32_32x32x16_bf16 v[16:31], v[78:81], v[66:69], v[16:31]
	v_cvt_pk_bf16_f32 v66, v106, v108
	v_cvt_pk_bf16_f32 v67, v109, v110
	v_cvt_pk_bf16_f32 v68, v111, v128
	v_cvt_pk_bf16_f32 v69, v129, v130
	v_cvt_pk_bf16_f32 v73, v136, v137
	ds_read_b128 v[74:77], v105 offset:27712
	ds_read_b128 v[78:81], v105 offset:27728
	ds_read_b128 v[98:101], v105 offset:32320
	ds_read_b128 v[102:105], v105 offset:32336
	s_waitcnt lgkmcnt(0)
	v_mfma_f32_32x32x16_bf16 v[48:63], v[82:85], v[66:69], v[48:63]
	v_mfma_f32_32x32x16_bf16 v[0:15], v[90:93], v[66:69], v[0:15]
	v_mfma_f32_32x32x16_bf16 v[48:63], v[86:89], v[70:73], v[48:63]
	v_mfma_f32_32x32x16_bf16 v[0:15], v[94:97], v[70:73], v[0:15]
	v_mfma_f32_32x32x16_bf16 v[32:47], v[74:77], v[66:69], v[32:47]
	v_mfma_f32_32x32x16_bf16 v[16:31], v[98:101], v[66:69], v[16:31]
	v_mfma_f32_32x32x16_bf16 v[32:47], v[78:81], v[70:73], v[32:47]
	v_mfma_f32_32x32x16_bf16 v[16:31], v[102:105], v[70:73], v[16:31]
	v_add_f32_e32 v66, 0, v106
	v_add_f32_e32 v66, v108, v66
	v_add_f32_e32 v66, v109, v66
	v_add_f32_e32 v66, v110, v66
	v_add_f32_e32 v66, v111, v66
	v_add_f32_e32 v66, v128, v66
	v_add_f32_e32 v66, v129, v66
	v_add_f32_e32 v66, v130, v66
	v_add_f32_e32 v65, v65, v66
	v_add_f32_e32 v65, v131, v65
	v_add_f32_e32 v65, v132, v65
	v_add_f32_e32 v65, v133, v65
	v_add_f32_e32 v65, v134, v65
	v_add_f32_e32 v65, v135, v65
	v_add_f32_e32 v65, v136, v65
	v_add_f32_e32 v65, v137, v65
	v_mov_b32_e32 v106, v177
	s_add_i32 s4, s20, s88
	s_waitcnt lgkmcnt(0)
	s_barrier
	v_pk_add_f32 v[156:157], v[64:65], v[106:107]
	v_add_u32_e32 v65, s4, v140
	v_sub_f32_e32 v64, v142, v156
	v_sub_u32_e32 v65, v146, v65
	v_add_u32_e32 v164, 64, v65
	s_mov_b32 s87, 0
	s_sub_i32 s91, 0, s4
	s_mov_b32 s8, 1
	s_mov_b32 s9, 0x9000
	s_mov_b64 s[46:47], s[10:11]
	s_mov_b64 s[40:41], s[76:77]
	s_mov_b32 s56, 0
	v_mov_b32_e32 v65, v64
	v_mov_b32_e32 v66, v64
	v_mov_b32_e32 v67, v64
	v_mov_b32_e32 v68, v64
	v_mov_b32_e32 v69, v64
	v_mov_b32_e32 v70, v64
	v_mov_b32_e32 v71, v64
	v_mov_b32_e32 v72, v64
	v_mov_b32_e32 v73, v64
	v_mov_b32_e32 v74, v64
	v_mov_b32_e32 v75, v64
	v_mov_b32_e32 v76, v64
	v_mov_b32_e32 v77, v64
	v_mov_b32_e32 v78, v64
	v_mov_b32_e32 v79, v64
	s_add_u32 vcc_lo, s46, 0xffffff80
	s_addc_u32 vcc_hi, s47, -1
	s_mov_b32 s16, 0x60000
	s_and_b64 s[4:5], s[52:53], exec
	s_cselect_b32 s17, s41, vcc_hi
	s_cselect_b32 s80, s40, vcc_lo
	s_cselect_b32 s81, 0x80, s16
	s_and_b64 s[4:5], s[48:49], exec
	s_cselect_b32 s17, s47, s17
	s_cselect_b32 s80, s46, s80
	s_cselect_b32 s81, s16, s81
	s_and_b64 s[4:5], s[36:37], exec
	s_cselect_b32 s5, vcc_hi, s17
	s_cselect_b32 s4, vcc_lo, s80
	s_cselect_b32 s81, s16, s81
	v_lshl_add_u64 v[240:241], s[4:5], 0, v[176:177]
	v_mov_b32_e32 v200, s81
	v_mov_b32_e32 v201, 0
	s_and_b64 s[4:5], s[28:29], exec
	s_cselect_b32 s17, s41, vcc_hi
	s_cselect_b32 s80, s40, vcc_lo
	s_cselect_b32 s81, 0x80, s16
	s_and_b64 s[4:5], s[66:67], exec
	s_cselect_b32 s17, s47, s17
	s_cselect_b32 s80, s46, s80
	s_cselect_b32 s81, s16, s81
	s_and_b64 s[4:5], s[50:51], exec
	s_cselect_b32 s5, vcc_hi, s17
	s_cselect_b32 s4, vcc_lo, s80
	s_cselect_b32 s81, s16, s81
	v_lshl_add_u64 v[242:243], s[4:5], 0, v[148:149]
	v_mov_b32_e32 v202, s81
	v_mov_b32_e32 v203, 0
	s_and_b64 s[4:5], s[60:61], exec
	s_cselect_b32 s17, s41, vcc_hi
	s_cselect_b32 s80, s40, vcc_lo
	s_cselect_b32 s81, 0x80, s16
	s_and_b64 s[4:5], s[38:39], exec
	s_cselect_b32 s17, s47, s17
	s_cselect_b32 s80, s46, s80
	s_cselect_b32 s81, s16, s81
	s_and_b64 s[4:5], s[62:63], exec
	s_cselect_b32 s5, vcc_hi, s17
	s_cselect_b32 s4, vcc_lo, s80
	s_cselect_b32 s81, s16, s81
	v_lshl_add_u64 v[244:245], s[4:5], 0, v[150:151]
	v_mov_b32_e32 v204, s81
	v_mov_b32_e32 v205, 0
	s_and_b64 s[4:5], s[6:7], exec
	s_cselect_b32 s17, s41, vcc_hi
	s_cselect_b32 s80, s40, vcc_lo
	s_cselect_b32 s81, 0x80, s16
	s_and_b64 s[4:5], s[12:13], exec
	s_cselect_b32 s17, s47, s17
	s_cselect_b32 s80, s46, s80
	s_cselect_b32 s81, s16, s81
	s_and_b64 s[4:5], s[22:23], exec
	s_cselect_b32 s5, vcc_hi, s17
	s_cselect_b32 s4, vcc_lo, s80
	s_cselect_b32 s81, s16, s81
	v_lshl_add_u64 v[246:247], s[4:5], 0, v[152:153]
	v_mov_b32_e32 v206, s81
	v_mov_b32_e32 v207, 0
	s_and_b64 s[4:5], s[14:15], exec
	s_cselect_b32 s17, s41, vcc_hi
	s_cselect_b32 s80, s40, vcc_lo
	s_cselect_b32 s81, 0x80, s16
	s_and_b64 s[4:5], s[0:1], exec
	s_cselect_b32 s17, s47, s17
	s_cselect_b32 s80, s46, s80
	s_cselect_b32 s81, s16, s81
	s_and_b64 s[4:5], s[68:69], exec
	s_cselect_b32 s5, vcc_hi, s17
	s_cselect_b32 s4, vcc_lo, s80
	s_cselect_b32 s81, s16, s81
	v_lshl_add_u64 v[248:249], s[4:5], 0, v[154:155]
	v_mov_b32_e32 v208, s81
	v_mov_b32_e32 v209, 0
	s_branch .LBB0_623

.LBB0_623:
	s_add_i32 s57, s9, 0
	s_add_i32 s4, s57, s94
	v_add_u32_e32 v80, s4, v162
	v_add_u32_e32 v84, v80, v146
	ds_read_b128 v[80:83], v84
	ds_read_b128 v[128:131], v84 offset:32
	ds_read_b128 v[136:139], v84 offset:4608
	ds_read_b128 v[132:135], v84 offset:4640
	s_cmp_gt_u32 s8, 61
	s_cselect_b64 s[78:79], -1, 0
	s_and_b64 vcc, exec, s[78:79]
	s_cbranch_vccnz .LBB0_625
	s_mul_i32 s16, s56, 0x9000
	s_add_i32 s17, s16, s35
	s_and_b64 s[80:81], s[54:55], exec
	s_cselect_b32 m0, s17, s82
	s_nop 0
	global_load_lds_dwordx4 v[240:241], off
	s_add_i32 s17, s16, s33
	s_and_b64 s[80:81], s[64:65], exec
	s_cselect_b32 m0, s17, s2
	v_lshl_add_u64 v[240:241], v[240:241], 0, v[200:201]
	global_load_lds_dwordx4 v[242:243], off
	s_add_i32 s17, s16, s93
	s_and_b64 s[80:81], s[42:43], exec
	s_cselect_b32 m0, s17, s92
	v_lshl_add_u64 v[242:243], v[242:243], 0, v[202:203]
	global_load_lds_dwordx4 v[244:245], off
	s_add_i32 s17, s16, s45
	s_and_b64 s[80:81], s[24:25], exec
	s_cselect_b32 m0, s17, s97
	v_lshl_add_u64 v[244:245], v[244:245], 0, v[204:205]
	global_load_lds_dwordx4 v[246:247], off
	s_add_i32 s17, s16, s59
	s_and_b64 s[80:81], s[70:71], exec
	s_cselect_b32 m0, s17, s27
	v_lshl_add_u64 v[246:247], v[246:247], 0, v[206:207]
	global_load_lds_dwordx4 v[248:249], off
	v_lshl_add_u64 v[248:249], v[248:249], 0, v[208:209]

.LBB0_637:
	s_nop 10
	v_max_f32_e32 v32, v1, v1
	v_max_f32_e32 v33, v17, v17
	v_max_f32_e32 v32, v33, v32
	v_max_f32_e32 v33, v2, v2
	v_max_f32_e32 v34, v18, v18
	v_max_f32_e32 v33, v34, v33
	v_max_f32_e32 v34, v3, v3
	v_max_f32_e32 v35, v19, v19
	v_max3_f32 v32, v16, v0, v32
	v_max_f32_e32 v34, v35, v34
	v_max3_f32 v32, v32, v33, v34
	v_max_f32_e32 v33, v4, v4
	v_max_f32_e32 v34, v20, v20
	v_max_f32_e32 v33, v34, v33
	v_max_f32_e32 v34, v5, v5
	v_max_f32_e32 v35, v21, v21
	v_max_f32_e32 v34, v35, v34
	v_max3_f32 v32, v32, v33, v34
	v_max_f32_e32 v33, v6, v6
	v_max_f32_e32 v34, v22, v22
	v_max_f32_e32 v33, v34, v33
	v_max_f32_e32 v34, v7, v7
	v_max_f32_e32 v35, v23, v23
	v_max_f32_e32 v34, v35, v34
	v_max3_f32 v32, v32, v33, v34
	v_max_f32_e32 v33, v8, v8
	v_max_f32_e32 v34, v24, v24
	v_max_f32_e32 v33, v34, v33
	v_max_f32_e32 v34, v9, v9
	v_max_f32_e32 v35, v25, v25
	v_max_f32_e32 v34, v35, v34
	v_max3_f32 v32, v32, v33, v34
	v_max_f32_e32 v33, v10, v10
	v_max_f32_e32 v34, v26, v26
	v_max_f32_e32 v33, v34, v33
	v_max_f32_e32 v34, v11, v11
	v_max_f32_e32 v35, v27, v27
	v_max_f32_e32 v34, v35, v34
	v_max3_f32 v32, v32, v33, v34
	v_max_f32_e32 v33, v12, v12
	v_max_f32_e32 v34, v28, v28
	v_max_f32_e32 v33, v34, v33
	v_max_f32_e32 v34, v13, v13
	v_max_f32_e32 v35, v29, v29
	v_max_f32_e32 v34, v35, v34
	v_max3_f32 v32, v32, v33, v34
	v_max_f32_e32 v33, v14, v14
	v_max_f32_e32 v34, v30, v30
	v_max_f32_e32 v33, v34, v33
	v_max_f32_e32 v34, v15, v15
	v_max_f32_e32 v35, v31, v31
	v_max_f32_e32 v34, v35, v34
	v_max3_f32 v32, v32, v33, v34
	v_mov_b32_e32 v33, v32
	s_nop 1
	v_permlane32_swap_b32_e32 v32, v33
	v_max_f32_e32 v33, v33, v33
	v_max_f32_e32 v32, v32, v32
	v_max_f32_e32 v64, v32, v33
	v_sub_f32_e32 v32, v0, v64
	v_sub_f32_e32 v0, v16, v64
	v_sub_f32_e32 v33, v1, v64
	v_sub_f32_e32 v1, v17, v64
	v_exp_f32_e32 v0, v0
	v_sub_f32_e32 v34, v2, v64
	v_sub_f32_e32 v2, v18, v64
	v_exp_f32_e32 v1, v1
	v_sub_f32_e32 v35, v3, v64
	v_sub_f32_e32 v3, v19, v64
	v_exp_f32_e32 v2, v2
	v_sub_f32_e32 v36, v4, v64
	v_sub_f32_e32 v4, v20, v64
	v_exp_f32_e32 v3, v3
	v_sub_f32_e32 v37, v5, v64
	v_sub_f32_e32 v5, v21, v64
	v_add_f32_e32 v16, 0, v0
	v_exp_f32_e32 v4, v4
	v_sub_f32_e32 v38, v6, v64
	v_sub_f32_e32 v6, v22, v64
	v_add_f32_e32 v16, v1, v16
	v_exp_f32_e32 v5, v5
	v_sub_f32_e32 v39, v7, v64
	v_sub_f32_e32 v7, v23, v64
	v_add_f32_e32 v16, v2, v16
	v_exp_f32_e32 v6, v6
	v_sub_f32_e32 v65, v8, v64
	v_sub_f32_e32 v8, v24, v64
	v_add_f32_e32 v16, v3, v16
	v_exp_f32_e32 v7, v7
	v_sub_f32_e32 v66, v9, v64
	v_sub_f32_e32 v9, v25, v64
	v_add_f32_e32 v16, v4, v16
	v_exp_f32_e32 v8, v8
	v_sub_f32_e32 v100, v10, v64
	v_sub_f32_e32 v10, v26, v64
	v_add_f32_e32 v16, v5, v16
	v_exp_f32_e32 v9, v9
	v_sub_f32_e32 v101, v11, v64
	v_sub_f32_e32 v11, v27, v64
	v_add_f32_e32 v16, v6, v16
	v_exp_f32_e32 v10, v10
	v_sub_f32_e32 v102, v12, v64
	v_sub_f32_e32 v12, v28, v64
	v_add_f32_e32 v16, v7, v16
	v_exp_f32_e32 v11, v11
	v_sub_f32_e32 v103, v13, v64
	v_sub_f32_e32 v13, v29, v64
	v_add_f32_e32 v16, v8, v16
	v_exp_f32_e32 v12, v12
	v_sub_f32_e32 v104, v14, v64
	v_sub_f32_e32 v14, v30, v64
	v_add_f32_e32 v16, v9, v16
	v_exp_f32_e32 v13, v13
	v_sub_f32_e32 v105, v15, v64
	v_sub_f32_e32 v15, v31, v64
	v_add_f32_e32 v16, v10, v16
	v_exp_f32_e32 v14, v14
	v_add_f32_e32 v16, v11, v16
	v_exp_f32_e32 v15, v15
	v_add_f32_e32 v16, v12, v16
	v_add_f32_e32 v16, v13, v16
	v_mul_u32_u24_e32 v164, 0x90, v140
	v_and_b32_e32 v165, 32, v141
	v_add_f32_e32 v16, v14, v16
	v_add_f32_e32 v16, v15, v16
	s_waitcnt lgkmcnt(0)
	s_barrier
	v_add3_u32 v106, 0, v164, v165
	v_add_f32_e32 v67, 0, v16
	v_cvt_pk_bf16_f32 v16, v0, v1
	v_cvt_pk_bf16_f32 v17, v2, v3
	v_cvt_pk_bf16_f32 v18, v4, v5
	v_cvt_pk_bf16_f32 v19, v6, v7
	ds_read_b128 v[0:3], v106 offset:18432
	ds_read_b128 v[20:23], v106 offset:18448
	ds_read_b128 v[4:7], v106 offset:23040
	ds_read_b128 v[24:27], v106 offset:23056
	v_cvt_pk_bf16_f32 v68, v8, v9
	v_cvt_pk_bf16_f32 v69, v10, v11
	v_cvt_pk_bf16_f32 v70, v12, v13
	v_cvt_pk_bf16_f32 v71, v14, v15
	s_add_u32 s33, s21, 0xc0000
	s_addc_u32 s40, s84, 0
	s_add_u32 s41, s44, 0x100
	s_addc_u32 s42, s85, 0
	s_add_u32 s21, s21, 0xc0080
	s_addc_u32 s24, s84, 0
	s_and_b64 s[0:1], s[52:53], exec
	s_cselect_b32 s2, s42, s40
	s_cselect_b32 s4, s41, s33
	s_and_b64 s[0:1], s[48:49], exec
	s_cselect_b32 s4, s21, s4
	s_cselect_b32 s2, s24, s2
	s_and_b64 s[0:1], s[36:37], exec
	s_cselect_b32 s1, s40, s2
	s_cselect_b32 s0, s33, s4
	s_add_i32 m0, s26, 0x12000
	s_or_b32 s4, s3, 8
	s_cmp_lt_i32 s4, 9
	v_lshl_add_u64 v[8:9], s[0:1], 0, v[176:177]
	s_cselect_b64 s[0:1], -1, 0
	s_cmp_lt_u32 s4, 18
	s_cselect_b64 s[6:7], -1, 0
	s_cmp_lt_u32 s4, 36
	s_cselect_b64 s[12:13], -1, 0
	s_and_b64 s[8:9], s[12:13], exec
	s_cselect_b32 s2, s42, s40
	s_cselect_b32 s5, s41, s33
	s_and_b64 s[8:9], s[6:7], exec
	s_cselect_b32 s5, s21, s5
	s_cselect_b32 s2, s24, s2
	s_and_b64 s[8:9], s[0:1], exec
	s_cselect_b32 s9, s40, s2
	s_cselect_b32 s8, s33, s5
	s_lshl_b32 s2, s4, 10
	s_add_i32 s2, s2, 0
	global_load_lds_dwordx4 v[8:9], off
	s_add_i32 m0, s2, 0x12000
	s_or_b32 s5, s3, 16
	s_cmp_lt_u32 s5, 18
	s_cselect_b64 s[14:15], -1, 0
	s_cmp_lt_u32 s5, 36
	s_cselect_b64 s[22:23], -1, 0
	v_lshl_add_u64 v[8:9], s[8:9], 0, v[148:149]
	s_and_b64 s[8:9], s[22:23], exec
	s_cselect_b32 s25, s41, s33
	s_cselect_b32 s26, s42, s40
	s_and_b64 s[8:9], s[14:15], exec
	s_cselect_b32 s9, s24, s26
	s_cselect_b32 s8, s21, s25
	s_lshl_b32 s21, s5, 10
	global_load_lds_dwordx4 v[8:9], off
	v_lshl_add_u64 v[8:9], s[8:9], 0, v[150:151]
	s_add_i32 s8, s21, 0
	s_add_i32 m0, s8, 0x12000
	s_or_b32 s9, s3, 24
	s_cmp_lt_u32 s9, 36
	s_cselect_b64 s[24:25], -1, 0
	s_and_b64 s[26:27], s[24:25], exec
	s_cselect_b32 s27, s42, s40
	s_cselect_b32 s26, s41, s33
	s_lshl_b32 s8, s9, 10
	global_load_lds_dwordx4 v[8:9], off
	v_lshl_add_u64 v[8:9], s[26:27], 0, v[152:153]
	s_add_i32 s26, s8, 0
	s_add_i32 m0, s26, 0x12000
	s_or_b32 s27, s3, 32
	s_cmp_lt_u32 s27, 36
	s_cselect_b64 s[28:29], -1, 0
	s_and_b64 s[38:39], s[28:29], exec
	s_cselect_b32 s39, s42, s40
	s_cselect_b32 s38, s41, s33
	s_lshl_b32 s3, s27, 10
	s_add_i32 s8, s3, 0
	global_load_lds_dwordx4 v[8:9], off
	v_lshl_add_u64 v[8:9], s[38:39], 0, v[154:155]
	s_add_i32 m0, s8, 0x12000
	s_nop 0
	global_load_lds_dwordx4 v[8:9], off
	ds_read_b128 v[28:31], v106 offset:27648
	ds_read_b128 v[72:75], v106 offset:27664
	ds_read_b128 v[76:79], v106 offset:32256
	ds_read_b128 v[80:83], v106 offset:32272
	s_waitcnt lgkmcnt(0)
	v_mfma_f32_32x32x16_bf16 v[48:63], v[0:3], v[16:19], 0
	v_exp_f32_e32 v107, v32
	v_exp_f32_e32 v108, v33
	v_exp_f32_e32 v109, v34
	v_exp_f32_e32 v110, v35
	v_add_f32_e32 v32, 0, v107
	v_add_f32_e32 v32, v108, v32
	v_add_f32_e32 v32, v109, v32
	v_mfma_f32_32x32x16_bf16 v[0:15], v[4:7], v[16:19], 0
	v_add_f32_e32 v32, v110, v32
	v_mfma_f32_32x32x16_bf16 v[48:63], v[20:23], v[68:71], v[48:63]
	v_exp_f32_e32 v111, v36
	v_exp_f32_e32 v128, v37
	v_exp_f32_e32 v129, v38
	v_exp_f32_e32 v130, v39
	v_add_f32_e32 v20, v111, v32
	v_add_f32_e32 v20, v128, v20
	v_add_f32_e32 v20, v129, v20
	v_mfma_f32_32x32x16_bf16 v[0:15], v[24:27], v[68:71], v[0:15]
	v_add_f32_e32 v20, v130, v20
	ds_read_b128 v[84:87], v106 offset:18496
	ds_read_b128 v[88:91], v106 offset:18512
	ds_read_b128 v[92:95], v106 offset:23104
	ds_read_b128 v[96:99], v106 offset:23120
	v_exp_f32_e32 v131, v65
	v_exp_f32_e32 v132, v66
	v_exp_f32_e32 v100, v100
	v_exp_f32_e32 v101, v101
	v_add_f32_e32 v20, v131, v20
	v_add_f32_e32 v20, v132, v20
	v_add_f32_e32 v20, v100, v20
	v_mfma_f32_32x32x16_bf16 v[32:47], v[28:31], v[16:19], 0
	v_add_f32_e32 v65, v101, v20
	v_mfma_f32_32x32x16_bf16 v[16:31], v[76:79], v[16:19], 0
	v_mfma_f32_32x32x16_bf16 v[32:47], v[72:75], v[68:71], v[32:47]
	v_exp_f32_e32 v72, v102
	v_exp_f32_e32 v73, v103
	v_exp_f32_e32 v74, v104
	v_exp_f32_e32 v75, v105
	v_add_f32_e32 v65, v72, v65
	v_add_f32_e32 v65, v73, v65
	v_add_f32_e32 v65, v74, v65
	v_mfma_f32_32x32x16_bf16 v[16:31], v[80:83], v[68:71], v[16:31]
	v_add_f32_e32 v65, v75, v65
	v_mov_b32_e32 v66, v177
	v_add_f32_e64 v156, v64, v66
	v_add_f32_e64 v157, v65, v67
	v_cvt_pk_bf16_f32 v66, v107, v108
	v_sub_f32_e32 v64, v163, v156
	v_cvt_pk_bf16_f32 v67, v109, v110
	v_cvt_pk_bf16_f32 v68, v111, v128
	v_cvt_pk_bf16_f32 v69, v129, v130
	v_cvt_pk_bf16_f32 v70, v131, v132
	v_cvt_pk_bf16_f32 v71, v100, v101
	v_cvt_pk_bf16_f32 v72, v72, v73
	v_cvt_pk_bf16_f32 v73, v74, v75
	ds_read_b128 v[74:77], v106 offset:27712
	ds_read_b128 v[78:81], v106 offset:27728
	ds_read_b128 v[100:103], v106 offset:32320
	ds_read_b128 v[104:107], v106 offset:32336
	s_waitcnt lgkmcnt(0)
	v_mfma_f32_32x32x16_bf16 v[48:63], v[84:87], v[66:69], v[48:63]
	v_mfma_f32_32x32x16_bf16 v[0:15], v[92:95], v[66:69], v[0:15]
	v_mfma_f32_32x32x16_bf16 v[48:63], v[88:91], v[70:73], v[48:63]
	v_mfma_f32_32x32x16_bf16 v[0:15], v[96:99], v[70:73], v[0:15]
	v_mfma_f32_32x32x16_bf16 v[32:47], v[74:77], v[66:69], v[32:47]
	v_mfma_f32_32x32x16_bf16 v[16:31], v[100:103], v[66:69], v[16:31]
	v_mfma_f32_32x32x16_bf16 v[32:47], v[78:81], v[70:73], v[32:47]
	v_mfma_f32_32x32x16_bf16 v[16:31], v[104:107], v[70:73], v[16:31]
	s_cmp_lt_i32 s4, 36
	s_cselect_b64 s[38:39], -1, 0
	s_cmp_lt_i32 s5, 36
	s_cselect_b64 s[40:41], -1, 0
	s_or_b32 s8, s21, 0x12000
	s_cmp_lt_i32 s9, 36
	s_cselect_b64 s[42:43], -1, 0
	s_cmp_lt_i32 s27, 36
	s_cselect_b64 s[46:47], -1, 0
	s_add_i32 s4, s20, s88
	s_waitcnt vmcnt(5) lgkmcnt(0)
	s_barrier
	v_add_u32_e32 v65, s4, v140
	v_sub_u32_e32 v65, v146, v65
	s_or_b32 s9, s3, 0x12000
	v_add_u32_e32 v166, 64, v65
	s_mov_b32 s20, 0
	s_sub_i32 s27, 0, s4
	s_mov_b32 s33, 1
	s_mov_b32 s44, 0x9000
	s_mov_b32 s45, 0
	v_mov_b32_e32 v65, v64
	v_mov_b32_e32 v66, v64
	v_mov_b32_e32 v67, v64
	v_mov_b32_e32 v68, v64
	v_mov_b32_e32 v69, v64
	v_mov_b32_e32 v70, v64
	v_mov_b32_e32 v71, v64
	v_mov_b32_e32 v72, v64
	v_mov_b32_e32 v73, v64
	v_mov_b32_e32 v74, v64
	v_mov_b32_e32 v75, v64
	v_mov_b32_e32 v76, v64
	v_mov_b32_e32 v77, v64
	v_mov_b32_e32 v78, v64
	v_mov_b32_e32 v79, v64
	s_add_u32 s59, s10, 0xffffff80
	s_addc_u32 s62, s11, -1
	s_mov_b32 s63, 0x60000
	s_and_b64 s[56:57], s[52:53], exec
	s_cselect_b32 s61, s77, s62
	s_cselect_b32 s60, s76, s59
	s_cselect_b32 s64, 0x80, s63
	s_and_b64 s[56:57], s[48:49], exec
	s_cselect_b32 s61, s11, s61
	s_cselect_b32 s60, s10, s60
	s_cselect_b32 s64, s63, s64
	s_and_b64 s[56:57], s[36:37], exec
	s_cselect_b32 s57, s62, s61
	s_cselect_b32 s56, s59, s60
	s_cselect_b32 s64, s63, s64
	v_lshl_add_u64 v[240:241], s[56:57], 0, v[176:177]
	v_mov_b32_e32 v200, s64
	v_mov_b32_e32 v201, 0
	s_and_b64 s[56:57], s[12:13], exec
	s_cselect_b32 s61, s77, s62
	s_cselect_b32 s60, s76, s59
	s_cselect_b32 s64, 0x80, s63
	s_and_b64 s[56:57], s[6:7], exec
	s_cselect_b32 s61, s11, s61
	s_cselect_b32 s60, s10, s60
	s_cselect_b32 s64, s63, s64
	s_and_b64 s[56:57], s[0:1], exec
	s_cselect_b32 s57, s62, s61
	s_cselect_b32 s56, s59, s60
	s_cselect_b32 s64, s63, s64
	v_lshl_add_u64 v[242:243], s[56:57], 0, v[148:149]
	v_mov_b32_e32 v202, s64
	v_mov_b32_e32 v203, 0
	s_and_b64 s[56:57], s[22:23], exec
	s_cselect_b32 s61, s77, s62
	s_cselect_b32 s60, s76, s59
	s_cselect_b32 s64, 0x80, s63
	s_and_b64 s[56:57], s[14:15], exec
	s_cselect_b32 s57, s11, s61
	s_cselect_b32 s56, s10, s60
	s_cselect_b32 s64, s63, s64
	v_lshl_add_u64 v[244:245], s[56:57], 0, v[150:151]
	v_mov_b32_e32 v204, s64
	v_mov_b32_e32 v205, 0
	s_and_b64 s[56:57], s[24:25], exec
	s_cselect_b32 s57, s77, s62
	s_cselect_b32 s56, s76, s59
	s_cselect_b32 s64, 0x80, s63
	v_lshl_add_u64 v[246:247], s[56:57], 0, v[152:153]
	v_mov_b32_e32 v206, s64
	v_mov_b32_e32 v207, 0
	s_and_b64 s[56:57], s[28:29], exec
	s_cselect_b32 s57, s77, s62
	s_cselect_b32 s56, s76, s59
	s_cselect_b32 s64, 0x80, s63
	v_lshl_add_u64 v[248:249], s[56:57], 0, v[154:155]
	v_mov_b32_e32 v208, s64
	v_mov_b32_e32 v209, 0
	s_branch .LBB0_639

.LBB0_643:
	v_add_u32_e32 v128, s50, v164
	s_waitcnt lgkmcnt(0)
	s_barrier
	v_add_u32_e32 v168, v128, v165
	ds_read_b128 v[140:143], v168 offset:18432
	ds_read_b128 v[132:135], v168 offset:18448
	ds_read_b128 v[136:139], v168 offset:23040
	ds_read_b128 v[128:131], v168 offset:23056
	s_cmp_gt_u32 s33, 61
	s_cselect_b64 s[50:51], -1, 0
	s_and_b64 vcc, exec, s[50:51]
	s_cbranch_vccnz .LBB0_645
	s_mul_i32 s63, s45, 0x9000
	s_or_b32 s64, s63, s35
	s_and_b64 s[60:61], s[54:55], exec
	s_cselect_b32 m0, s64, s82
	s_nop 0
	global_load_lds_dwordx4 v[240:241], off
	s_and_b64 s[60:61], s[38:39], exec
	s_cselect_b32 s60, s63, 0x12000
	s_add_i32 m0, s2, s60
	v_lshl_add_u64 v[240:241], v[240:241], 0, v[200:201]
	global_load_lds_dwordx4 v[242:243], off
	s_add_i32 s64, s63, s21
	s_and_b64 s[60:61], s[40:41], exec
	s_cselect_b32 m0, s64, s8
	v_lshl_add_u64 v[242:243], v[242:243], 0, v[202:203]
	global_load_lds_dwordx4 v[244:245], off
	s_and_b64 s[60:61], s[42:43], exec
	s_cselect_b32 s60, s63, 0x12000
	s_add_i32 m0, s26, s60
	v_lshl_add_u64 v[244:245], v[244:245], 0, v[204:205]
	global_load_lds_dwordx4 v[246:247], off
	s_add_i32 s63, s63, s3
	s_and_b64 s[60:61], s[46:47], exec
	s_cselect_b32 m0, s63, s9
	v_lshl_add_u64 v[246:247], v[246:247], 0, v[206:207]
	global_load_lds_dwordx4 v[248:249], off
	v_lshl_add_u64 v[248:249], v[248:249], 0, v[208:209]

.LBB0_682:
	s_nop 10
	v_max_f32_e32 v32, v1, v1
	v_max_f32_e32 v33, v17, v17
	v_max_f32_e32 v32, v33, v32
	v_max_f32_e32 v33, v2, v2
	v_max_f32_e32 v34, v18, v18
	v_max_f32_e32 v33, v34, v33
	v_max_f32_e32 v34, v3, v3
	v_max_f32_e32 v35, v19, v19
	v_max3_f32 v32, v16, v0, v32
	v_max_f32_e32 v34, v35, v34
	v_max3_f32 v32, v32, v33, v34
	v_max_f32_e32 v33, v4, v4
	v_max_f32_e32 v34, v20, v20
	v_max_f32_e32 v33, v34, v33
	v_max_f32_e32 v34, v5, v5
	v_max_f32_e32 v35, v21, v21
	v_max_f32_e32 v34, v35, v34
	v_max3_f32 v32, v32, v33, v34
	v_max_f32_e32 v33, v6, v6
	v_max_f32_e32 v34, v22, v22
	v_max_f32_e32 v33, v34, v33
	v_max_f32_e32 v34, v7, v7
	v_max_f32_e32 v35, v23, v23
	v_max_f32_e32 v34, v35, v34
	v_max3_f32 v32, v32, v33, v34
	v_max_f32_e32 v33, v8, v8
	v_max_f32_e32 v34, v24, v24
	v_max_f32_e32 v33, v34, v33
	v_max_f32_e32 v34, v9, v9
	v_max_f32_e32 v35, v25, v25
	v_max_f32_e32 v34, v35, v34
	v_max3_f32 v32, v32, v33, v34
	v_max_f32_e32 v33, v10, v10
	v_max_f32_e32 v34, v26, v26
	v_max_f32_e32 v33, v34, v33
	v_max_f32_e32 v34, v11, v11
	v_max_f32_e32 v35, v27, v27
	v_max_f32_e32 v34, v35, v34
	v_max3_f32 v32, v32, v33, v34
	v_max_f32_e32 v33, v12, v12
	v_max_f32_e32 v34, v28, v28
	v_max_f32_e32 v33, v34, v33
	v_max_f32_e32 v34, v13, v13
	v_max_f32_e32 v35, v29, v29
	v_max_f32_e32 v34, v35, v34
	v_max3_f32 v32, v32, v33, v34
	v_max_f32_e32 v33, v14, v14
	v_max_f32_e32 v34, v30, v30
	v_max_f32_e32 v33, v34, v33
	v_max_f32_e32 v34, v15, v15
	v_max_f32_e32 v35, v31, v31
	v_max_f32_e32 v34, v35, v34
	v_max3_f32 v32, v32, v33, v34
	v_mov_b32_e32 v33, v32
	s_nop 1
	v_permlane32_swap_b32_e32 v32, v33
	v_max_f32_e32 v33, v33, v33
	v_max_f32_e32 v32, v32, v32
	v_max_f32_e32 v64, v32, v33
	v_sub_f32_e32 v32, v0, v64
	v_sub_f32_e32 v0, v16, v64
	v_sub_f32_e32 v33, v1, v64
	v_sub_f32_e32 v1, v17, v64
	v_exp_f32_e32 v0, v0
	v_sub_f32_e32 v34, v2, v64
	v_sub_f32_e32 v2, v18, v64
	v_exp_f32_e32 v1, v1
	v_sub_f32_e32 v35, v3, v64
	v_sub_f32_e32 v3, v19, v64
	v_exp_f32_e32 v2, v2
	v_sub_f32_e32 v36, v4, v64
	v_sub_f32_e32 v4, v20, v64
	v_exp_f32_e32 v3, v3
	v_sub_f32_e32 v37, v5, v64
	v_sub_f32_e32 v5, v21, v64
	v_add_f32_e32 v16, 0, v0
	v_exp_f32_e32 v4, v4
	v_sub_f32_e32 v38, v6, v64
	v_sub_f32_e32 v6, v22, v64
	v_add_f32_e32 v16, v1, v16
	v_exp_f32_e32 v5, v5
	v_sub_f32_e32 v39, v7, v64
	v_sub_f32_e32 v7, v23, v64
	v_add_f32_e32 v16, v2, v16
	v_exp_f32_e32 v6, v6
	v_sub_f32_e32 v65, v8, v64
	v_sub_f32_e32 v8, v24, v64
	v_add_f32_e32 v16, v3, v16
	v_exp_f32_e32 v7, v7
	v_sub_f32_e32 v98, v9, v64
	v_sub_f32_e32 v9, v25, v64
	v_add_f32_e32 v16, v4, v16
	v_exp_f32_e32 v8, v8
	v_sub_f32_e32 v99, v10, v64
	v_sub_f32_e32 v10, v26, v64
	v_add_f32_e32 v16, v5, v16
	v_exp_f32_e32 v9, v9
	v_sub_f32_e32 v100, v11, v64
	v_sub_f32_e32 v11, v27, v64
	v_add_f32_e32 v16, v6, v16
	v_exp_f32_e32 v10, v10
	v_sub_f32_e32 v101, v12, v64
	v_sub_f32_e32 v12, v28, v64
	v_add_f32_e32 v16, v7, v16
	v_exp_f32_e32 v11, v11
	v_sub_f32_e32 v102, v13, v64
	v_sub_f32_e32 v13, v29, v64
	v_add_f32_e32 v16, v8, v16
	v_exp_f32_e32 v12, v12
	v_sub_f32_e32 v103, v14, v64
	v_sub_f32_e32 v14, v30, v64
	v_add_f32_e32 v16, v9, v16
	v_exp_f32_e32 v13, v13
	v_sub_f32_e32 v104, v15, v64
	v_sub_f32_e32 v15, v31, v64
	v_add_f32_e32 v16, v10, v16
	v_exp_f32_e32 v14, v14
	v_add_f32_e32 v16, v11, v16
	v_exp_f32_e32 v15, v15
	v_add_f32_e32 v16, v12, v16
	v_add_f32_e32 v16, v13, v16
	v_mul_u32_u24_e32 v143, 0x90, v140
	v_and_b32_e32 v163, 32, v141
	v_add_f32_e32 v16, v14, v16
	v_add_f32_e32 v16, v15, v16
	s_waitcnt vmcnt(5) lgkmcnt(0)
	s_barrier
	v_add3_u32 v105, 0, v143, v163
	v_add_f32_e32 v107, 0, v16
	v_cvt_pk_bf16_f32 v16, v0, v1
	v_cvt_pk_bf16_f32 v17, v2, v3
	v_cvt_pk_bf16_f32 v18, v4, v5
	v_cvt_pk_bf16_f32 v19, v6, v7
	ds_read_b128 v[0:3], v105 offset:18432
	ds_read_b128 v[20:23], v105 offset:18448
	ds_read_b128 v[4:7], v105 offset:23040
	ds_read_b128 v[24:27], v105 offset:23056
	v_cvt_pk_bf16_f32 v66, v8, v9
	v_cvt_pk_bf16_f32 v67, v10, v11
	v_cvt_pk_bf16_f32 v68, v12, v13
	v_cvt_pk_bf16_f32 v69, v14, v15
	ds_read_b128 v[28:31], v105 offset:27648
	ds_read_b128 v[70:73], v105 offset:27664
	ds_read_b128 v[74:77], v105 offset:32256
	ds_read_b128 v[78:81], v105 offset:32272
	s_waitcnt lgkmcnt(0)
	v_mfma_f32_32x32x16_bf16 v[48:63], v[0:3], v[16:19], 0
	v_exp_f32_e32 v106, v32
	v_exp_f32_e32 v108, v33
	v_exp_f32_e32 v109, v34
	v_exp_f32_e32 v110, v35
	v_mfma_f32_32x32x16_bf16 v[0:15], v[4:7], v[16:19], 0
	v_mfma_f32_32x32x16_bf16 v[48:63], v[20:23], v[66:69], v[48:63]
	v_exp_f32_e32 v111, v36
	v_exp_f32_e32 v128, v37
	v_exp_f32_e32 v129, v38
	v_exp_f32_e32 v130, v39
	v_mfma_f32_32x32x16_bf16 v[0:15], v[24:27], v[66:69], v[0:15]
	ds_read_b128 v[82:85], v105 offset:18496
	ds_read_b128 v[86:89], v105 offset:18512
	ds_read_b128 v[90:93], v105 offset:23104
	ds_read_b128 v[94:97], v105 offset:23120
	v_mfma_f32_32x32x16_bf16 v[32:47], v[28:31], v[16:19], 0
	v_exp_f32_e32 v65, v65
	v_exp_f32_e32 v131, v98
	v_exp_f32_e32 v132, v99
	v_exp_f32_e32 v133, v100
	v_mfma_f32_32x32x16_bf16 v[16:31], v[74:77], v[16:19], 0
	v_mfma_f32_32x32x16_bf16 v[32:47], v[70:73], v[66:69], v[32:47]
	v_exp_f32_e32 v134, v101
	v_exp_f32_e32 v135, v102
	v_exp_f32_e32 v136, v103
	v_exp_f32_e32 v137, v104
	v_cvt_pk_bf16_f32 v70, v65, v131
	v_cvt_pk_bf16_f32 v71, v132, v133
	v_cvt_pk_bf16_f32 v72, v134, v135
	v_mfma_f32_32x32x16_bf16 v[16:31], v[78:81], v[66:69], v[16:31]
	v_cvt_pk_bf16_f32 v66, v106, v108
	v_cvt_pk_bf16_f32 v67, v109, v110
	v_cvt_pk_bf16_f32 v68, v111, v128
	v_cvt_pk_bf16_f32 v69, v129, v130
	v_cvt_pk_bf16_f32 v73, v136, v137
	ds_read_b128 v[74:77], v105 offset:27712
	ds_read_b128 v[78:81], v105 offset:27728
	ds_read_b128 v[98:101], v105 offset:32320
	ds_read_b128 v[102:105], v105 offset:32336
	s_waitcnt lgkmcnt(0)
	v_mfma_f32_32x32x16_bf16 v[48:63], v[82:85], v[66:69], v[48:63]
	v_mfma_f32_32x32x16_bf16 v[0:15], v[90:93], v[66:69], v[0:15]
	v_mfma_f32_32x32x16_bf16 v[48:63], v[86:89], v[70:73], v[48:63]
	v_mfma_f32_32x32x16_bf16 v[0:15], v[94:97], v[70:73], v[0:15]
	v_mfma_f32_32x32x16_bf16 v[32:47], v[74:77], v[66:69], v[32:47]
	v_mfma_f32_32x32x16_bf16 v[16:31], v[98:101], v[66:69], v[16:31]
	v_mfma_f32_32x32x16_bf16 v[32:47], v[78:81], v[70:73], v[32:47]
	v_mfma_f32_32x32x16_bf16 v[16:31], v[102:105], v[70:73], v[16:31]
	v_add_f32_e32 v66, 0, v106
	v_add_f32_e32 v66, v108, v66
	v_add_f32_e32 v66, v109, v66
	v_add_f32_e32 v66, v110, v66
	v_add_f32_e32 v66, v111, v66
	v_add_f32_e32 v66, v128, v66
	v_add_f32_e32 v66, v129, v66
	v_add_f32_e32 v66, v130, v66
	v_add_f32_e32 v65, v65, v66
	v_add_f32_e32 v65, v131, v65
	v_add_f32_e32 v65, v132, v65
	v_add_f32_e32 v65, v133, v65
	v_add_f32_e32 v65, v134, v65
	v_add_f32_e32 v65, v135, v65
	v_add_f32_e32 v65, v136, v65
	v_add_f32_e32 v65, v137, v65
	v_mov_b32_e32 v106, v177
	s_add_i32 s4, s20, s88
	s_waitcnt lgkmcnt(0)
	s_barrier
	v_pk_add_f32 v[156:157], v[64:65], v[106:107]
	v_add_u32_e32 v65, s4, v140
	v_sub_f32_e32 v64, v142, v156
	v_sub_u32_e32 v65, v146, v65
	v_add_u32_e32 v164, 64, v65
	s_mov_b32 s58, 0
	s_sub_i32 s91, 0, s4
	s_mov_b32 s8, 1
	s_mov_b32 s9, 0x9000
	s_mov_b64 s[10:11], s[46:47]
	s_mov_b64 s[76:77], s[40:41]
	s_mov_b32 s56, 0
	v_mov_b32_e32 v65, v64
	v_mov_b32_e32 v66, v64
	v_mov_b32_e32 v67, v64
	v_mov_b32_e32 v68, v64
	v_mov_b32_e32 v69, v64
	v_mov_b32_e32 v70, v64
	v_mov_b32_e32 v71, v64
	v_mov_b32_e32 v72, v64
	v_mov_b32_e32 v73, v64
	v_mov_b32_e32 v74, v64
	v_mov_b32_e32 v75, v64
	v_mov_b32_e32 v76, v64
	v_mov_b32_e32 v77, v64
	v_mov_b32_e32 v78, v64
	v_mov_b32_e32 v79, v64
	s_add_u32 s16, s10, 0xffffff80
	s_addc_u32 s17, s11, -1
	s_mov_b32 vcc_lo, 0x60000
	s_and_b64 s[4:5], s[52:53], exec
	s_cselect_b32 s80, s77, s17
	s_cselect_b32 s81, s76, s16
	s_cselect_b32 vcc_hi, 0x80, vcc_lo
	s_and_b64 s[4:5], s[48:49], exec
	s_cselect_b32 s80, s11, s80
	s_cselect_b32 s81, s10, s81
	s_cselect_b32 vcc_hi, vcc_lo, vcc_hi
	s_and_b64 s[4:5], s[36:37], exec
	s_cselect_b32 s5, s17, s80
	s_cselect_b32 s4, s16, s81
	s_cselect_b32 vcc_hi, vcc_lo, vcc_hi
	v_lshl_add_u64 v[240:241], s[4:5], 0, v[176:177]
	v_mov_b32_e32 v200, vcc_hi
	v_mov_b32_e32 v201, 0
	s_and_b64 s[4:5], s[28:29], exec
	s_cselect_b32 s80, s77, s17
	s_cselect_b32 s81, s76, s16
	s_cselect_b32 vcc_hi, 0x80, vcc_lo
	s_and_b64 s[4:5], s[66:67], exec
	s_cselect_b32 s80, s11, s80
	s_cselect_b32 s81, s10, s81
	s_cselect_b32 vcc_hi, vcc_lo, vcc_hi
	s_and_b64 s[4:5], s[50:51], exec
	s_cselect_b32 s5, s17, s80
	s_cselect_b32 s4, s16, s81
	s_cselect_b32 vcc_hi, vcc_lo, vcc_hi
	v_lshl_add_u64 v[242:243], s[4:5], 0, v[148:149]
	v_mov_b32_e32 v202, vcc_hi
	v_mov_b32_e32 v203, 0
	s_and_b64 s[4:5], s[60:61], exec
	s_cselect_b32 s80, s77, s17
	s_cselect_b32 s81, s76, s16
	s_cselect_b32 vcc_hi, 0x80, vcc_lo
	s_and_b64 s[4:5], s[38:39], exec
	s_cselect_b32 s80, s11, s80
	s_cselect_b32 s81, s10, s81
	s_cselect_b32 vcc_hi, vcc_lo, vcc_hi
	s_and_b64 s[4:5], s[62:63], exec
	s_cselect_b32 s5, s17, s80
	s_cselect_b32 s4, s16, s81
	s_cselect_b32 vcc_hi, vcc_lo, vcc_hi
	v_lshl_add_u64 v[244:245], s[4:5], 0, v[150:151]
	v_mov_b32_e32 v204, vcc_hi
	v_mov_b32_e32 v205, 0
	s_and_b64 s[4:5], s[6:7], exec
	s_cselect_b32 s80, s77, s17
	s_cselect_b32 s81, s76, s16
	s_cselect_b32 vcc_hi, 0x80, vcc_lo
	s_and_b64 s[4:5], s[12:13], exec
	s_cselect_b32 s80, s11, s80
	s_cselect_b32 s81, s10, s81
	s_cselect_b32 vcc_hi, vcc_lo, vcc_hi
	s_and_b64 s[4:5], s[22:23], exec
	s_cselect_b32 s5, s17, s80
	s_cselect_b32 s4, s16, s81
	s_cselect_b32 vcc_hi, vcc_lo, vcc_hi
	v_lshl_add_u64 v[246:247], s[4:5], 0, v[152:153]
	v_mov_b32_e32 v206, vcc_hi
	v_mov_b32_e32 v207, 0
	s_and_b64 s[4:5], s[14:15], exec
	s_cselect_b32 s80, s77, s17
	s_cselect_b32 s81, s76, s16
	s_cselect_b32 vcc_hi, 0x80, vcc_lo
	s_and_b64 s[4:5], s[0:1], exec
	s_cselect_b32 s80, s11, s80
	s_cselect_b32 s81, s10, s81
	s_cselect_b32 vcc_hi, vcc_lo, vcc_hi
	s_and_b64 s[4:5], s[68:69], exec
	s_cselect_b32 s5, s17, s80
	s_cselect_b32 s4, s16, s81
	s_cselect_b32 vcc_hi, vcc_lo, vcc_hi
	v_lshl_add_u64 v[248:249], s[4:5], 0, v[154:155]
	v_mov_b32_e32 v208, vcc_hi
	v_mov_b32_e32 v209, 0
	s_branch .LBB0_684

.LBB0_684:
	s_add_i32 s57, s9, 0
	s_add_i32 s4, s57, s94
	v_add_u32_e32 v80, s4, v162
	v_add_u32_e32 v84, v80, v146
	ds_read_b128 v[80:83], v84
	ds_read_b128 v[128:131], v84 offset:32
	ds_read_b128 v[136:139], v84 offset:4608
	ds_read_b128 v[132:135], v84 offset:4640
	s_cmp_gt_u32 s8, 29
	s_cselect_b64 s[78:79], -1, 0
	s_and_b64 vcc, exec, s[78:79]
	s_cbranch_vccnz .LBB0_686
	s_mul_i32 vcc_lo, s56, 0x9000
	s_add_i32 vcc_hi, vcc_lo, s35
	s_and_b64 s[80:81], s[54:55], exec
	s_cselect_b32 m0, vcc_hi, s82
	s_nop 0
	global_load_lds_dwordx4 v[240:241], off
	s_add_i32 vcc_hi, vcc_lo, s33
	s_and_b64 s[80:81], s[64:65], exec
	s_cselect_b32 m0, vcc_hi, s2
	v_lshl_add_u64 v[240:241], v[240:241], 0, v[200:201]
	global_load_lds_dwordx4 v[242:243], off
	s_add_i32 vcc_hi, vcc_lo, s93
	s_and_b64 s[80:81], s[42:43], exec
	s_cselect_b32 m0, vcc_hi, s92
	v_lshl_add_u64 v[242:243], v[242:243], 0, v[202:203]
	global_load_lds_dwordx4 v[244:245], off
	s_add_i32 vcc_hi, vcc_lo, s45
	s_and_b64 s[80:81], s[24:25], exec
	s_cselect_b32 m0, vcc_hi, s97
	v_lshl_add_u64 v[244:245], v[244:245], 0, v[204:205]
	global_load_lds_dwordx4 v[246:247], off
	s_add_i32 vcc_hi, vcc_lo, s59
	s_and_b64 s[80:81], s[70:71], exec
	s_cselect_b32 m0, vcc_hi, s86
	v_lshl_add_u64 v[246:247], v[246:247], 0, v[206:207]
	global_load_lds_dwordx4 v[248:249], off
	v_lshl_add_u64 v[248:249], v[248:249], 0, v[208:209]

.LBB0_698:
	s_nop 10
	v_max_f32_e32 v32, v1, v1
	v_max_f32_e32 v33, v17, v17
	v_max_f32_e32 v32, v33, v32
	v_max_f32_e32 v33, v2, v2
	v_max_f32_e32 v34, v18, v18
	v_max_f32_e32 v33, v34, v33
	v_max_f32_e32 v34, v3, v3
	v_max_f32_e32 v35, v19, v19
	v_max3_f32 v32, v16, v0, v32
	v_max_f32_e32 v34, v35, v34
	v_max3_f32 v32, v32, v33, v34
	v_max_f32_e32 v33, v4, v4
	v_max_f32_e32 v34, v20, v20
	v_max_f32_e32 v33, v34, v33
	v_max_f32_e32 v34, v5, v5
	v_max_f32_e32 v35, v21, v21
	v_max_f32_e32 v34, v35, v34
	v_max3_f32 v32, v32, v33, v34
	v_max_f32_e32 v33, v6, v6
	v_max_f32_e32 v34, v22, v22
	v_max_f32_e32 v33, v34, v33
	v_max_f32_e32 v34, v7, v7
	v_max_f32_e32 v35, v23, v23
	v_max_f32_e32 v34, v35, v34
	v_max3_f32 v32, v32, v33, v34
	v_max_f32_e32 v33, v8, v8
	v_max_f32_e32 v34, v24, v24
	v_max_f32_e32 v33, v34, v33
	v_max_f32_e32 v34, v9, v9
	v_max_f32_e32 v35, v25, v25
	v_max_f32_e32 v34, v35, v34
	v_max3_f32 v32, v32, v33, v34
	v_max_f32_e32 v33, v10, v10
	v_max_f32_e32 v34, v26, v26
	v_max_f32_e32 v33, v34, v33
	v_max_f32_e32 v34, v11, v11
	v_max_f32_e32 v35, v27, v27
	v_max_f32_e32 v34, v35, v34
	v_max3_f32 v32, v32, v33, v34
	v_max_f32_e32 v33, v12, v12
	v_max_f32_e32 v34, v28, v28
	v_max_f32_e32 v33, v34, v33
	v_max_f32_e32 v34, v13, v13
	v_max_f32_e32 v35, v29, v29
	v_max_f32_e32 v34, v35, v34
	v_max3_f32 v32, v32, v33, v34
	v_max_f32_e32 v33, v14, v14
	v_max_f32_e32 v34, v30, v30
	v_max_f32_e32 v33, v34, v33
	v_max_f32_e32 v34, v15, v15
	v_max_f32_e32 v35, v31, v31
	v_max_f32_e32 v34, v35, v34
	v_max3_f32 v32, v32, v33, v34
	v_mov_b32_e32 v33, v32
	s_nop 1
	v_permlane32_swap_b32_e32 v32, v33
	v_max_f32_e32 v33, v33, v33
	v_max_f32_e32 v32, v32, v32
	v_max_f32_e32 v64, v32, v33
	v_sub_f32_e32 v32, v0, v64
	v_sub_f32_e32 v0, v16, v64
	v_sub_f32_e32 v33, v1, v64
	v_sub_f32_e32 v1, v17, v64
	v_exp_f32_e32 v0, v0
	v_sub_f32_e32 v34, v2, v64
	v_sub_f32_e32 v2, v18, v64
	v_exp_f32_e32 v1, v1
	v_sub_f32_e32 v35, v3, v64
	v_sub_f32_e32 v3, v19, v64
	v_exp_f32_e32 v2, v2
	v_sub_f32_e32 v36, v4, v64
	v_sub_f32_e32 v4, v20, v64
	v_exp_f32_e32 v3, v3
	v_sub_f32_e32 v37, v5, v64
	v_sub_f32_e32 v5, v21, v64
	v_add_f32_e32 v16, 0, v0
	v_exp_f32_e32 v4, v4
	v_sub_f32_e32 v38, v6, v64
	v_sub_f32_e32 v6, v22, v64
	v_add_f32_e32 v16, v1, v16
	v_exp_f32_e32 v5, v5
	v_sub_f32_e32 v39, v7, v64
	v_sub_f32_e32 v7, v23, v64
	v_add_f32_e32 v16, v2, v16
	v_exp_f32_e32 v6, v6
	v_sub_f32_e32 v65, v8, v64
	v_sub_f32_e32 v8, v24, v64
	v_add_f32_e32 v16, v3, v16
	v_exp_f32_e32 v7, v7
	v_sub_f32_e32 v66, v9, v64
	v_sub_f32_e32 v9, v25, v64
	v_add_f32_e32 v16, v4, v16
	v_exp_f32_e32 v8, v8
	v_sub_f32_e32 v100, v10, v64
	v_sub_f32_e32 v10, v26, v64
	v_add_f32_e32 v16, v5, v16
	v_exp_f32_e32 v9, v9
	v_sub_f32_e32 v101, v11, v64
	v_sub_f32_e32 v11, v27, v64
	v_add_f32_e32 v16, v6, v16
	v_exp_f32_e32 v10, v10
	v_sub_f32_e32 v102, v12, v64
	v_sub_f32_e32 v12, v28, v64
	v_add_f32_e32 v16, v7, v16
	v_exp_f32_e32 v11, v11
	v_sub_f32_e32 v103, v13, v64
	v_sub_f32_e32 v13, v29, v64
	v_add_f32_e32 v16, v8, v16
	v_exp_f32_e32 v12, v12
	v_sub_f32_e32 v104, v14, v64
	v_sub_f32_e32 v14, v30, v64
	v_add_f32_e32 v16, v9, v16
	v_exp_f32_e32 v13, v13
	v_sub_f32_e32 v105, v15, v64
	v_sub_f32_e32 v15, v31, v64
	v_add_f32_e32 v16, v10, v16
	v_exp_f32_e32 v14, v14
	v_add_f32_e32 v16, v11, v16
	v_exp_f32_e32 v15, v15
	v_add_f32_e32 v16, v12, v16
	v_add_f32_e32 v16, v13, v16
	v_mul_u32_u24_e32 v164, 0x90, v140
	v_and_b32_e32 v165, 32, v141
	v_add_f32_e32 v16, v14, v16
	v_add_f32_e32 v16, v15, v16
	s_waitcnt lgkmcnt(0)
	s_barrier
	v_add3_u32 v106, 0, v164, v165
	v_add_f32_e32 v67, 0, v16
	v_cvt_pk_bf16_f32 v16, v0, v1
	v_cvt_pk_bf16_f32 v17, v2, v3
	v_cvt_pk_bf16_f32 v18, v4, v5
	v_cvt_pk_bf16_f32 v19, v6, v7
	ds_read_b128 v[0:3], v106 offset:18432
	ds_read_b128 v[20:23], v106 offset:18448
	ds_read_b128 v[4:7], v106 offset:23040
	ds_read_b128 v[24:27], v106 offset:23056
	v_cvt_pk_bf16_f32 v68, v8, v9
	v_cvt_pk_bf16_f32 v69, v10, v11
	v_cvt_pk_bf16_f32 v70, v12, v13
	v_cvt_pk_bf16_f32 v71, v14, v15
	s_add_u32 s16, s21, 0xc0000
	s_addc_u32 s17, s84, 0
	s_add_u32 s33, s44, 0x100
	s_addc_u32 s38, s85, 0
	s_add_u32 s10, s21, 0xc0080
	s_addc_u32 s11, s84, 0
	s_and_b64 s[0:1], s[52:53], exec
	s_cselect_b32 s2, s38, s17
	s_cselect_b32 s4, s33, s16
	s_and_b64 s[0:1], s[48:49], exec
	s_cselect_b32 s4, s10, s4
	s_cselect_b32 s2, s11, s2
	s_and_b64 s[0:1], s[36:37], exec
	s_cselect_b32 s1, s17, s2
	s_cselect_b32 s0, s16, s4
	s_add_i32 m0, s26, 0x12000
	s_or_b32 s4, s3, 8
	s_cmp_lt_i32 s4, 9
	v_lshl_add_u64 v[8:9], s[0:1], 0, v[176:177]
	s_cselect_b64 s[0:1], -1, 0
	s_cmp_lt_u32 s4, 18
	s_cselect_b64 s[6:7], -1, 0
	s_cmp_lt_u32 s4, 36
	s_cselect_b64 s[12:13], -1, 0
	s_and_b64 s[8:9], s[12:13], exec
	s_cselect_b32 s2, s38, s17
	s_cselect_b32 s5, s33, s16
	s_and_b64 s[8:9], s[6:7], exec
	s_cselect_b32 s5, s10, s5
	s_cselect_b32 s2, s11, s2
	s_and_b64 s[8:9], s[0:1], exec
	s_cselect_b32 s9, s17, s2
	s_cselect_b32 s8, s16, s5
	s_lshl_b32 s2, s4, 10
	s_add_i32 s2, s2, 0
	global_load_lds_dwordx4 v[8:9], off
	s_add_i32 m0, s2, 0x12000
	s_or_b32 s5, s3, 16
	s_cmp_lt_u32 s5, 18
	s_cselect_b64 s[14:15], -1, 0
	s_cmp_lt_u32 s5, 36
	s_cselect_b64 s[22:23], -1, 0
	v_lshl_add_u64 v[8:9], s[8:9], 0, v[148:149]
	s_and_b64 s[8:9], s[22:23], exec
	s_cselect_b32 s21, s33, s16
	s_cselect_b32 s24, s38, s17
	s_and_b64 s[8:9], s[14:15], exec
	s_cselect_b32 s9, s11, s24
	s_cselect_b32 s8, s10, s21
	s_lshl_b32 s21, s5, 10
	global_load_lds_dwordx4 v[8:9], off
	v_lshl_add_u64 v[8:9], s[8:9], 0, v[150:151]
	s_add_i32 s8, s21, 0
	s_add_i32 m0, s8, 0x12000
	s_or_b32 s9, s3, 24
	s_cmp_lt_u32 s9, 36
	s_cselect_b64 s[24:25], -1, 0
	s_and_b64 s[10:11], s[24:25], exec
	s_cselect_b32 s11, s38, s17
	s_cselect_b32 s10, s33, s16
	s_lshl_b32 s8, s9, 10
	s_add_i32 s26, s8, 0
	global_load_lds_dwordx4 v[8:9], off
	s_add_i32 m0, s26, 0x12000
	s_or_b32 s27, s3, 32
	s_cmp_lt_u32 s27, 36
	s_cselect_b64 s[28:29], -1, 0
	v_lshl_add_u64 v[8:9], s[10:11], 0, v[152:153]
	s_and_b64 s[10:11], s[28:29], exec
	s_cselect_b32 s11, s38, s17
	s_cselect_b32 s10, s33, s16
	s_lshl_b32 s3, s27, 10
	s_add_i32 s8, s3, 0
	global_load_lds_dwordx4 v[8:9], off
	v_lshl_add_u64 v[8:9], s[10:11], 0, v[154:155]
	s_add_i32 m0, s8, 0x12000
	s_nop 0
	global_load_lds_dwordx4 v[8:9], off
	ds_read_b128 v[28:31], v106 offset:27648
	ds_read_b128 v[72:75], v106 offset:27664
	ds_read_b128 v[76:79], v106 offset:32256
	ds_read_b128 v[80:83], v106 offset:32272
	s_waitcnt lgkmcnt(0)
	v_mfma_f32_32x32x16_bf16 v[48:63], v[0:3], v[16:19], 0
	v_exp_f32_e32 v107, v32
	v_exp_f32_e32 v108, v33
	v_exp_f32_e32 v109, v34
	v_exp_f32_e32 v110, v35
	v_add_f32_e32 v32, 0, v107
	v_add_f32_e32 v32, v108, v32
	v_add_f32_e32 v32, v109, v32
	v_mfma_f32_32x32x16_bf16 v[0:15], v[4:7], v[16:19], 0
	v_add_f32_e32 v32, v110, v32
	v_mfma_f32_32x32x16_bf16 v[48:63], v[20:23], v[68:71], v[48:63]
	v_exp_f32_e32 v111, v36
	v_exp_f32_e32 v128, v37
	v_exp_f32_e32 v129, v38
	v_exp_f32_e32 v130, v39
	v_add_f32_e32 v20, v111, v32
	v_add_f32_e32 v20, v128, v20
	v_add_f32_e32 v20, v129, v20
	v_mfma_f32_32x32x16_bf16 v[0:15], v[24:27], v[68:71], v[0:15]
	v_add_f32_e32 v20, v130, v20
	ds_read_b128 v[84:87], v106 offset:18496
	ds_read_b128 v[88:91], v106 offset:18512
	ds_read_b128 v[92:95], v106 offset:23104
	ds_read_b128 v[96:99], v106 offset:23120
	v_exp_f32_e32 v131, v65
	v_exp_f32_e32 v132, v66
	v_exp_f32_e32 v100, v100
	v_exp_f32_e32 v101, v101
	v_add_f32_e32 v20, v131, v20
	v_add_f32_e32 v20, v132, v20
	v_add_f32_e32 v20, v100, v20
	v_mfma_f32_32x32x16_bf16 v[32:47], v[28:31], v[16:19], 0
	v_add_f32_e32 v65, v101, v20
	v_mfma_f32_32x32x16_bf16 v[16:31], v[76:79], v[16:19], 0
	v_mfma_f32_32x32x16_bf16 v[32:47], v[72:75], v[68:71], v[32:47]
	v_exp_f32_e32 v72, v102
	v_exp_f32_e32 v73, v103
	v_exp_f32_e32 v74, v104
	v_exp_f32_e32 v75, v105
	v_add_f32_e32 v65, v72, v65
	v_add_f32_e32 v65, v73, v65
	v_add_f32_e32 v65, v74, v65
	v_mfma_f32_32x32x16_bf16 v[16:31], v[80:83], v[68:71], v[16:31]
	v_add_f32_e32 v65, v75, v65
	v_mov_b32_e32 v66, v177
	v_add_f32_e64 v156, v64, v66
	v_add_f32_e64 v157, v65, v67
	v_cvt_pk_bf16_f32 v66, v107, v108
	v_sub_f32_e32 v64, v163, v156
	v_cvt_pk_bf16_f32 v67, v109, v110
	v_cvt_pk_bf16_f32 v68, v111, v128
	v_cvt_pk_bf16_f32 v69, v129, v130
	v_cvt_pk_bf16_f32 v70, v131, v132
	v_cvt_pk_bf16_f32 v71, v100, v101
	v_cvt_pk_bf16_f32 v72, v72, v73
	v_cvt_pk_bf16_f32 v73, v74, v75
	ds_read_b128 v[74:77], v106 offset:27712
	ds_read_b128 v[78:81], v106 offset:27728
	ds_read_b128 v[100:103], v106 offset:32320
	ds_read_b128 v[104:107], v106 offset:32336
	s_waitcnt lgkmcnt(0)
	v_mfma_f32_32x32x16_bf16 v[48:63], v[84:87], v[66:69], v[48:63]
	v_mfma_f32_32x32x16_bf16 v[0:15], v[92:95], v[66:69], v[0:15]
	v_mfma_f32_32x32x16_bf16 v[48:63], v[88:91], v[70:73], v[48:63]
	v_mfma_f32_32x32x16_bf16 v[0:15], v[96:99], v[70:73], v[0:15]
	v_mfma_f32_32x32x16_bf16 v[32:47], v[74:77], v[66:69], v[32:47]
	v_mfma_f32_32x32x16_bf16 v[16:31], v[100:103], v[66:69], v[16:31]
	v_mfma_f32_32x32x16_bf16 v[32:47], v[78:81], v[70:73], v[32:47]
	v_mfma_f32_32x32x16_bf16 v[16:31], v[104:107], v[70:73], v[16:31]
	s_cmp_lt_i32 s4, 36
	s_cselect_b64 s[10:11], -1, 0
	s_cmp_lt_i32 s5, 36
	s_cselect_b64 s[38:39], -1, 0
	s_or_b32 s8, s21, 0x12000
	s_cmp_lt_i32 s9, 36
	s_cselect_b64 s[42:43], -1, 0
	s_cmp_lt_i32 s27, 36
	s_cselect_b64 s[50:51], -1, 0
	s_add_i32 s4, s20, s88
	s_waitcnt vmcnt(5) lgkmcnt(0)
	s_barrier
	v_add_u32_e32 v65, s4, v140
	v_sub_u32_e32 v65, v146, v65
	s_or_b32 s9, s3, 0x12000
	v_add_u32_e32 v166, 64, v65
	s_mov_b32 s20, 0
	s_sub_i32 s27, 0, s4
	s_mov_b32 s33, 1
	s_mov_b32 s44, 0x9000
	s_mov_b32 s45, 0
	v_mov_b32_e32 v65, v64
	v_mov_b32_e32 v66, v64
	v_mov_b32_e32 v67, v64
	v_mov_b32_e32 v68, v64
	v_mov_b32_e32 v69, v64
	v_mov_b32_e32 v70, v64
	v_mov_b32_e32 v71, v64
	v_mov_b32_e32 v72, v64
	v_mov_b32_e32 v73, v64
	v_mov_b32_e32 v74, v64
	v_mov_b32_e32 v75, v64
	v_mov_b32_e32 v76, v64
	v_mov_b32_e32 v77, v64
	v_mov_b32_e32 v78, v64
	v_mov_b32_e32 v79, v64
	s_add_u32 s16, s46, 0xffffff80
	s_addc_u32 s17, s47, -1
	s_mov_b32 s62, 0x60000
	s_and_b64 s[56:57], s[52:53], exec
	s_cselect_b32 s59, s41, s17
	s_cselect_b32 s58, s40, s16
	s_cselect_b32 s63, 0x80, s62
	s_and_b64 s[56:57], s[48:49], exec
	s_cselect_b32 s59, s47, s59
	s_cselect_b32 s58, s46, s58
	s_cselect_b32 s63, s62, s63
	s_and_b64 s[56:57], s[36:37], exec
	s_cselect_b32 s57, s17, s59
	s_cselect_b32 s56, s16, s58
	s_cselect_b32 s63, s62, s63
	v_lshl_add_u64 v[240:241], s[56:57], 0, v[176:177]
	v_mov_b32_e32 v200, s63
	v_mov_b32_e32 v201, 0
	s_and_b64 s[56:57], s[12:13], exec
	s_cselect_b32 s59, s41, s17
	s_cselect_b32 s58, s40, s16
	s_cselect_b32 s63, 0x80, s62
	s_and_b64 s[56:57], s[6:7], exec
	s_cselect_b32 s59, s47, s59
	s_cselect_b32 s58, s46, s58
	s_cselect_b32 s63, s62, s63
	s_and_b64 s[56:57], s[0:1], exec
	s_cselect_b32 s57, s17, s59
	s_cselect_b32 s56, s16, s58
	s_cselect_b32 s63, s62, s63
	v_lshl_add_u64 v[242:243], s[56:57], 0, v[148:149]
	v_mov_b32_e32 v202, s63
	v_mov_b32_e32 v203, 0
	s_and_b64 s[56:57], s[22:23], exec
	s_cselect_b32 s59, s41, s17
	s_cselect_b32 s58, s40, s16
	s_cselect_b32 s63, 0x80, s62
	s_and_b64 s[56:57], s[14:15], exec
	s_cselect_b32 s57, s47, s59
	s_cselect_b32 s56, s46, s58
	s_cselect_b32 s63, s62, s63
	v_lshl_add_u64 v[244:245], s[56:57], 0, v[150:151]
	v_mov_b32_e32 v204, s63
	v_mov_b32_e32 v205, 0
	s_and_b64 s[56:57], s[24:25], exec
	s_cselect_b32 s57, s41, s17
	s_cselect_b32 s56, s40, s16
	s_cselect_b32 s63, 0x80, s62
	v_lshl_add_u64 v[246:247], s[56:57], 0, v[152:153]
	v_mov_b32_e32 v206, s63
	v_mov_b32_e32 v207, 0
	s_and_b64 s[56:57], s[28:29], exec
	s_cselect_b32 s57, s41, s17
	s_cselect_b32 s56, s40, s16
	s_cselect_b32 s63, 0x80, s62
	v_lshl_add_u64 v[248:249], s[56:57], 0, v[154:155]
	v_mov_b32_e32 v208, s63
	v_mov_b32_e32 v209, 0
	s_branch .LBB0_700

.LBB0_704:
	v_add_u32_e32 v128, s56, v164
	s_waitcnt lgkmcnt(0)
	s_barrier
	v_add_u32_e32 v168, v128, v165
	ds_read_b128 v[140:143], v168 offset:18432
	ds_read_b128 v[132:135], v168 offset:18448
	ds_read_b128 v[136:139], v168 offset:23040
	ds_read_b128 v[128:131], v168 offset:23056
	s_cmp_gt_u32 s33, 29
	s_cselect_b64 s[60:61], -1, 0
	s_and_b64 vcc, exec, s[60:61]
	s_cbranch_vccnz .LBB0_706
	s_mul_i32 s62, s45, 0x9000
	s_or_b32 s63, s62, s35
	s_and_b64 s[58:59], s[54:55], exec
	s_cselect_b32 m0, s63, s82
	s_nop 0
	global_load_lds_dwordx4 v[240:241], off
	s_and_b64 s[58:59], s[10:11], exec
	s_cselect_b32 s58, s62, 0x12000
	s_add_i32 m0, s2, s58
	v_lshl_add_u64 v[240:241], v[240:241], 0, v[200:201]
	global_load_lds_dwordx4 v[242:243], off
	s_add_i32 s63, s62, s21
	s_and_b64 s[58:59], s[38:39], exec
	s_cselect_b32 m0, s63, s8
	v_lshl_add_u64 v[242:243], v[242:243], 0, v[202:203]
	global_load_lds_dwordx4 v[244:245], off
	s_and_b64 s[58:59], s[42:43], exec
	s_cselect_b32 s58, s62, 0x12000
	s_add_i32 m0, s26, s58
	v_lshl_add_u64 v[244:245], v[244:245], 0, v[204:205]
	global_load_lds_dwordx4 v[246:247], off
	s_add_i32 s62, s62, s3
	s_and_b64 s[58:59], s[50:51], exec
	s_cselect_b32 m0, s62, s9
	v_lshl_add_u64 v[246:247], v[246:247], 0, v[206:207]
	global_load_lds_dwordx4 v[248:249], off
	v_lshl_add_u64 v[248:249], v[248:249], 0, v[208:209]
